# grid barrier: two extra un-waited L2 write-backs (local arrivers nloc/2 and 3*nloc/4)
# speedup vs baseline: 1.0017x; 1.0017x over previous
.LBB0_41:
	s_or_b64 exec, exec, s[6:7]
	v_cvt_f32_u32_e32 v6, v4
	s_waitcnt vmcnt(0)
	v_readfirstlane_b32 s6, v5
	v_sub_u32_e32 v5, 0, v4
	v_rcp_iflag_f32_e32 v6, v6
	v_add_u32_e32 v7, s6, v2
	v_mul_f32_e32 v6, 0x4f7ffffe, v6
	v_cvt_u32_f32_e32 v6, v6
	v_mul_lo_u32 v2, v5, v6
	v_mul_hi_u32 v2, v6, v2
	v_add_u32_e32 v2, v6, v2
	v_mul_hi_u32 v2, v7, v2
	v_mul_lo_u32 v5, v2, v4
	v_sub_u32_e32 v5, v7, v5
	v_add_u32_e32 v6, 1, v2
	v_sub_u32_e32 v8, v5, v4
	v_cmp_ge_u32_e32 vcc, v5, v4
	s_nop 1
	v_cndmask_b32_e32 v2, v2, v6, vcc
	v_cndmask_b32_e32 v5, v5, v8, vcc
	v_add_u32_e32 v6, 1, v2
	v_cmp_ge_u32_e32 vcc, v5, v4
	v_add_u32_e32 v5, 1, v7
	s_nop 0
	v_cndmask_b32_e32 v2, v2, v6, vcc
	v_mul_lo_u32 v6, v4, v2
	v_add_u32_e32 v4, v6, v4
	v_cmp_ne_u32_e32 vcc, v5, v4
	s_and_saveexec_b64 s[6:7], vcc
	s_xor_b64 s[6:7], exec, s[6:7]
	s_cbranch_execz .LBB0_55
	v_sub_u32_e32 v8, v4, v6
	v_sub_u32_e32 v6, v7, v6
	v_lshrrev_b32_e32 v9, 2, v8
	v_lshrrev_b32_e32 v10, 1, v8
	v_sub_u32_e32 v8, v8, v9
	v_cmp_eq_u32_e32 vcc, v6, v8
	v_cmp_eq_u32_e64 s[12:13], v6, v10
	s_or_b64 vcc, vcc, s[12:13]
	s_cbranch_vccz .Lbar_nomidwb
	buffer_wbl2 sc1
